# zback: lines of the item three iterations ahead touched by scratch loads issued behind the counted weight loads; bottom waits re-derived
# speedup vs baseline: 1.0049x; 1.0037x over previous
.LBB0_491:
	s_or_b64 exec, exec, s[4:5]
	s_and_b64 s[4:5], s[2:3], exec
	v_lshl_add_u32 v20, s0, 10, v42
	s_cselect_b32 s0, s17, 0x19fa0000
	s_add_u32 s4, s64, s0
	v_ashrrev_i32_e32 v43, 31, v42
	s_addc_u32 s5, s65, 0
	s_and_b64 s[2:3], s[2:3], exec
	v_lshlrev_b64 v[50:51], 2, v[42:43]
	v_ashrrev_i32_e32 v21, 31, v20
	s_cselect_b32 s0, 14, 9
	v_lshl_add_u64 v[42:43], s[60:61], 0, v[50:51]
	v_lshlrev_b64 v[20:21], s0, v[20:21]
	v_add_co_u32_e32 v52, vcc, 0x3000, v42
	v_lshl_add_u64 v[20:21], s[4:5], 0, v[20:21]
	s_nop 0
	v_addc_co_u32_e32 v53, vcc, 0, v43, vcc
	v_lshl_add_u64 v[20:21], v[20:21], 0, v[38:39]
	v_add_co_u32_e32 v54, vcc, 0x6000, v42
	s_mov_b32 s98, 0x800
	s_mov_b32 s99, 0
	v_lshl_add_u64 v[248:249], v[20:21], 0, s[98:99]
	global_load_dwordx4 v[20:23], v[20:21], off
	s_nop 0
	v_addc_co_u32_e32 v55, vcc, 0, v43, vcc
	global_load_dword v38, v[42:43], off
	s_nop 0
	global_load_dword v42, v[52:53], off
	global_load_dword v43, v[54:55], off
	v_lshl_add_u64 v[50:51], s[62:63], 0, v[50:51]
	global_load_dword v50, v[50:51], off
	global_load_dwordx4 v[250:253], v[248:249], off
	global_load_dwordx4 v[250:253], v[246:247], off
.LBB0_492:
	v_lshlrev_b32_e32 v54, 16, v3
	v_lshlrev_b32_e32 v25, 16, v0
	v_and_b32_e32 v52, 0xffff0000, v2
	v_mov_b32_e32 v53, v54
	v_and_b32_e32 v0, 0xffff0000, v0
	v_and_b32_e32 v55, 0xffff0000, v3
	v_pk_fma_f32 v[58:59], v[32:33], v[52:53], v[34:35] op_sel_hi:[0,1,0]
	v_lshlrev_b32_e32 v60, 16, v5
	v_and_b32_e32 v61, 0xffff0000, v5
	v_lshlrev_b32_e32 v64, 16, v4
	v_and_b32_e32 v65, 0xffff0000, v4
	v_pk_fma_f32 v[4:5], v[32:33], v[24:25], v[34:35] op_sel_hi:[0,1,0]
	v_mov_b32_e32 v24, v25
	v_mov_b32_e32 v25, v0
	v_pk_fma_f32 v[58:59], v[28:29], v[54:55], v[58:59] op_sel_hi:[0,1,1]
	v_mov_b32_e32 v26, v55
	v_and_b32_e32 v55, 16, v2
	v_and_b32_e32 v54, 0xffff0000, v1
	v_lshlrev_b32_e32 v1, 16, v1
	v_pk_fma_f32 v[4:5], v[28:29], v[24:25], v[4:5] op_sel_hi:[0,1,1]
	v_pk_fma_f32 v[62:63], v[32:33], v[0:1], v[34:35] op_sel_hi:[0,1,0]
	v_pk_fma_f32 v[4:5], v[30:31], v[0:1], v[4:5] op_sel_hi:[0,1,1]
	v_pk_mov_b32 v[0:1], v[0:1], v[54:55] op_sel:[1,0]
	v_lshlrev_b32_e32 v3, 16, v2
	v_mov_b32_e32 v2, v54
	v_pk_fma_f32 v[0:1], v[28:29], v[0:1], v[62:63] op_sel_hi:[0,1,1]
	v_pk_fma_f32 v[0:1], v[30:31], v[2:3], v[0:1] op_sel_hi:[0,1,1]
	v_lshlrev_b32_e32 v56, 16, v7
	v_and_b32_e32 v57, 0xffff0000, v7
	v_pk_fma_f32 v[26:27], v[30:31], v[26:27], v[58:59] op_sel_hi:[0,1,1]
	v_lshlrev_b32_e32 v58, 16, v6
	v_and_b32_e32 v59, 0xffff0000, v6
	v_pk_fma_f32 v[6:7], v[32:33], v[2:3], v[34:35] op_sel_hi:[0,1,0]
	v_pk_mul_f32 v[24:25], v[0:1], v[60:61]
	v_pk_mov_b32 v[0:1], v[2:3], v[52:53] op_sel:[1,0]
	s_lshr_b32 s0, s19, 4
	v_pk_fma_f32 v[0:1], v[28:29], v[0:1], v[6:7] op_sel_hi:[0,1,1]
	v_pk_fma_f32 v[0:1], v[30:31], v[52:53], v[0:1] op_sel_hi:[0,1,1]
	v_pk_mul_f32 v[4:5], v[4:5], v[64:65]
	v_pk_mul_f32 v[2:3], v[0:1], v[58:59]
	v_pk_mul_f32 v[6:7], v[26:27], v[56:57]
	s_cmpk_lt_i32 s19, 0x4000
	v_cvt_pk_bf16_f32 v0, v4, v5
	v_cvt_pk_bf16_f32 v1, v24, v25
	v_cvt_pk_bf16_f32 v2, v2, v3
	v_cvt_pk_bf16_f32 v3, v6, v7
	s_cselect_b32 s2, 0x7f, 3
	s_barrier
	ds_write_b128 v46, v[0:3]
	s_waitcnt lgkmcnt(0)
	s_barrier
	ds_read_u16 v0, v47
	ds_read_u16 v1, v47 offset:144
	ds_read_u16 v2, v47 offset:288
	ds_read_u16 v3, v47 offset:432
	ds_read_u16 v4, v47 offset:576
	ds_read_u16 v5, v47 offset:720
	ds_read_u16 v6, v47 offset:864
	ds_read_u16 v7, v47 offset:1008
	s_cselect_b32 s3, s18, 0x7fffff00
	s_and_b32 s0, s2, s0
	s_and_b32 s2, s3, s13
	s_lshl_b32 s0, s0, 6
	s_waitcnt lgkmcnt(7)
	v_lshlrev_b32_e32 v0, 16, v0
	s_waitcnt lgkmcnt(6)
	v_lshlrev_b32_e32 v1, 16, v1
	s_waitcnt lgkmcnt(5)
	v_lshlrev_b32_e32 v2, 16, v2
	s_waitcnt lgkmcnt(4)
	v_lshlrev_b32_e32 v3, 16, v3
	s_waitcnt lgkmcnt(3)
	v_lshlrev_b32_e32 v4, 16, v4
	s_waitcnt lgkmcnt(2)
	v_lshlrev_b32_e32 v5, 16, v5
	s_add_i32 s0, s0, s2
	v_cvt_pk_bf16_f32 v0, v0, v1
	v_cvt_pk_bf16_f32 v1, v2, v3
	v_cvt_pk_bf16_f32 v2, v4, v5
	v_add_u32_e32 v4, s0, v29
	v_ashrrev_i32_e32 v5, 31, v4
	v_readlane_b32 s2, v243, 54
	v_lshlrev_b64 v[4:5], 11, v[4:5]
	v_readlane_b32 s3, v243, 55
	s_and_b32 s0, s11, 0x3c0
	s_lshl_b32 s0, s0, 1
	v_lshl_add_u64 v[4:5], s[2:3], 0, v[4:5]
	s_waitcnt lgkmcnt(1)
	v_lshlrev_b32_e32 v6, 16, v6
	s_waitcnt lgkmcnt(0)
	v_lshlrev_b32_e32 v7, 16, v7
	v_lshl_add_u64 v[4:5], v[4:5], 0, s[0:1]
	v_mov_b32_e32 v41, v39
	v_cvt_pk_bf16_f32 v3, v6, v7
	v_lshl_add_u64 v[4:5], v[4:5], 0, v[40:41]
	global_store_dwordx4 v[4:5], v[0:3], off
	s_add_i32 s19, s19, s66
	s_add_i32 s11, s11, s12
	s_add_i32 s13, s13, s14
	v_mov_b64_e32 v[0:1], v[16:17]
	v_mov_b64_e32 v[4:5], v[12:13]
	s_cmpk_lt_i32 s19, 0x4200
	v_mov_b32_e32 v34, v45
	v_mov_b32_e32 v30, v44
	v_mov_b32_e32 v28, v33
	v_mov_b32_e32 v32, v31
	s_waitcnt vmcnt(6)
	v_mov_b32_e32 v31, v38
	v_lshlrev_b32_e32 v35, 16, v244
	v_lshlrev_b32_e32 v37, 16, v245
	s_waitcnt vmcnt(5)
	v_mov_b32_e32 v33, v42
	s_waitcnt vmcnt(4)
	v_mov_b32_e32 v44, v43
	s_waitcnt vmcnt(3)
	v_mov_b32_e32 v45, v50
	v_mov_b64_e32 v[2:3], v[18:19]
	v_mov_b64_e32 v[6:7], v[14:15]
	v_mov_b32_e32 v24, v49
	v_mov_b32_e32 v27, v48
	s_cbranch_scc0 .LBB0_502

.LBB0_498:
	s_add_i32 s5, s15, s11
	v_lshl_or_b32 v22, s20, 6, v36
	v_readlane_b32 s20, v243, 56
	s_and_b32 s5, s5, 0x3c0
	v_readlane_b32 s21, v243, 57
	v_add_u32_e32 v42, s5, v29
	s_ashr_i32 s5, s4, 31
	v_mov_b64_e32 v[8:9], s[20:21]
	v_mad_i64_i32 v[8:9], s[20:21], v42, s16, v[8:9]
	v_lshl_add_u64 v[8:9], s[4:5], 1, v[8:9]
	v_lshlrev_b32_e32 v38, 1, v22
	v_lshl_add_u64 v[20:21], v[8:9], 0, v[38:39]
	global_load_dwordx4 v[8:11], v[20:21], off
	s_mov_b32 s98, 0x800
	s_mov_b32 s99, 0
	v_lshl_add_u64 v[246:247], v[20:21], 0, s[98:99]
	v_cmp_ne_u32_e32 vcc, 0, v22
	v_mov_b32_e32 v245, 0
	v_mov_b32_e32 v244, 0
	s_and_saveexec_b64 s[4:5], vcc
	s_cbranch_execz .LBB0_500
	global_load_ushort v244, v[20:21], off offset:-2
	s_nop 0
	s_nop 0
